# v2: + index next-unit q staging no longer waited right after issue; attention: 40 hazard-free s_nop removed
# speedup vs baseline: 1.0065x; 1.0065x over previous
.LBB0_1384:
	s_and_b64 s[0:1], s[60:61], exec
	s_cselect_b32 s8, s91, -1
	s_and_b64 s[0:1], s[62:63], exec
	s_cselect_b32 s8, s90, s8
	s_and_b64 s[0:1], exec, s[58:59]
	s_cselect_b32 s0, s23, s8
	s_cmp_gt_i32 s0, -1
	s_waitcnt lgkmcnt(0)
	s_barrier
	s_cbranch_scc0 .LBB0_1387
	s_waitcnt vmcnt(0)
	v_mov_b32_e32 v4, v36
	s_lshl_b32 s0, s0, 4
	s_and_b64 vcc, exec, s[40:41]
	v_and_or_b32 v2, v4, 15, s0
	v_or_b32_e32 v188, s92, v2
	v_readlane_b32 s0, v251, 44
	v_lshlrev_b64 v[2:3], 10, v[188:189]
	v_readlane_b32 s1, v251, 45
	v_ashrrev_i32_e32 v4, 1, v4
	v_and_b32_e32 v4, -8, v4
	v_lshl_add_u64 v[2:3], s[0:1], 0, v[2:3]
	v_readlane_b32 s0, v252, 28
	v_ashrrev_i32_e32 v5, 31, v4
	s_add_i32 s0, s0, 0
	v_lshl_add_u64 v[2:3], v[4:5], 1, v[2:3]
	s_add_i32 m0, s0, 0x22200
	s_nop 0
	global_load_lds_dwordx4 v[2:3], off
	v_lshl_add_u64 v[2:3], v[2:3], 0, 64
	s_add_i32 m0, s0, 0x22600
	s_nop 0
	global_load_lds_dwordx4 v[2:3], off
	s_cbranch_vccnz .Lix_staged
	v_readlane_b32 s0, v251, 29
	s_mov_b32 m0, s0
	v_readlane_b32 s0, v251, 46
	v_lshlrev_b64 v[2:3], 5, v[188:189]
	v_readlane_b32 s1, v251, 47
	s_nop 1
	v_lshl_add_u64 v[2:3], s[0:1], 0, v[2:3]
	v_readlane_b32 s0, v251, 30
	v_lshl_add_u64 v[4:5], v[2:3], 0, 16
	global_load_lds_dwordx4 v[2:3], off
	s_mov_b32 m0, s0
	s_nop 0
	global_load_lds_dwordx4 v[4:5], off
	s_branch .Lix_staged

.Lix_staged:
	v_lshlrev_b32_e32 v5, 5, v36
	s_sub_i32 s10, 0xff, s24
	s_mov_b32 s8, 0
	v_cmp_eq_u32_e64 s[40:41], 0, v36
	v_sub_u32_e32 v2, 0x7e0, v5
	s_mov_b64 s[0:1], -1
	s_branch .LBB0_1390

.LBB0_2977:
	v_lshrrev_b32_e32 v62, v232, v208
	v_lshrrev_b32_e32 v63, v232, v209
	s_waitcnt lgkmcnt(14)
	v_mfma_f32_32x32x16_bf16 v[34:49], v[142:145], v[178:181], v[34:49]
	v_exp_f32_e32 v58, v98
	v_bfe_i32 v98, v62, 0, 1
	v_and_b32 v98, v98, v58
	v_exp_f32_e32 v58, v99
	v_bfe_i32 v99, v62, 1, 1
	v_and_b32 v99, v99, v58
	v_exp_f32_e32 v58, v100
	v_bfe_i32 v100, v62, 2, 1
	v_and_b32 v100, v100, v58
	v_exp_f32_e32 v58, v101
	v_bfe_i32 v101, v62, 3, 1
	v_and_b32 v101, v101, v58
	s_waitcnt lgkmcnt(12)
	v_mfma_f32_32x32x16_bf16 v[18:33], v[142:145], v[174:177], v[18:33]
	v_exp_f32_e32 v58, v102
	v_bfe_i32 v102, v62, 8, 1
	v_and_b32 v102, v102, v58
	v_exp_f32_e32 v58, v103
	v_bfe_i32 v103, v62, 9, 1
	v_and_b32 v103, v103, v58
	v_exp_f32_e32 v58, v104
	v_bfe_i32 v104, v62, 10, 1
	v_and_b32 v104, v104, v58
	v_exp_f32_e32 v58, v105
	v_bfe_i32 v105, v62, 11, 1
	v_and_b32 v105, v105, v58
	v_add_u32_e32 v64, s24, v235
	ds_read_b128 v[58:61], v64
	ds_read_b128 v[146:149], v64 offset:512
	s_waitcnt lgkmcnt(12)
	v_mfma_f32_32x32x16_bf16 v[34:49], v[138:141], v[166:169], v[34:49]
	v_exp_f32_e32 v65, v106
	v_bfe_i32 v106, v62, 16, 1
	v_and_b32 v106, v106, v65
	v_exp_f32_e32 v65, v107
	v_bfe_i32 v107, v62, 17, 1
	v_and_b32 v107, v107, v65
	v_exp_f32_e32 v65, v108
	v_bfe_i32 v108, v62, 18, 1
	v_and_b32 v108, v108, v65
	v_exp_f32_e32 v65, v109
	v_bfe_i32 v109, v62, 19, 1
	v_and_b32 v109, v109, v65
	ds_read_b128 v[174:177], v64 offset:2048
	ds_read_b128 v[162:165], v64 offset:2560
	s_waitcnt lgkmcnt(12)
	v_mfma_f32_32x32x16_bf16 v[18:33], v[138:141], v[74:77], v[18:33]
	v_exp_f32_e32 v65, v110
	v_bfe_i32 v110, v62, 24, 1
	v_and_b32 v110, v110, v65
	v_exp_f32_e32 v65, v111
	v_bfe_i32 v111, v62, 25, 1
	v_and_b32 v111, v111, v65
	v_exp_f32_e32 v65, v112
	v_bfe_i32 v112, v62, 26, 1
	v_and_b32 v112, v112, v65
	v_exp_f32_e32 v65, v113
	v_bfe_i32 v113, v62, 27, 1
	v_and_b32 v113, v113, v65
	ds_read_b128 v[178:181], v64 offset:4096
	ds_read_b128 v[166:169], v64 offset:4608
	s_waitcnt lgkmcnt(12)
	v_mfma_f32_32x32x16_bf16 v[34:49], v[134:137], v[70:73], v[34:49]
	v_exp_f32_e32 v62, v82
	v_bfe_i32 v82, v63, 0, 1
	v_and_b32 v82, v82, v62
	v_exp_f32_e32 v62, v83
	v_bfe_i32 v83, v63, 1, 1
	v_and_b32 v83, v83, v62
	v_exp_f32_e32 v62, v84
	v_bfe_i32 v84, v63, 2, 1
	v_and_b32 v84, v84, v62
	v_exp_f32_e32 v62, v85
	v_bfe_i32 v85, v63, 3, 1
	v_and_b32 v85, v85, v62
	ds_read_b128 v[182:185], v64 offset:6144
	ds_read_b128 v[170:173], v64 offset:6656
	s_waitcnt lgkmcnt(12)
	v_mfma_f32_32x32x16_bf16 v[18:33], v[134:137], v[66:69], v[18:33]
	v_exp_f32_e32 v62, v86
	v_bfe_i32 v86, v63, 8, 1
	v_and_b32 v86, v86, v62
	v_exp_f32_e32 v62, v87
	v_bfe_i32 v87, v63, 9, 1
	v_and_b32 v87, v87, v62
	v_exp_f32_e32 v62, v88
	v_bfe_i32 v88, v63, 10, 1
	v_and_b32 v88, v88, v62
	v_exp_f32_e32 v62, v89
	v_bfe_i32 v89, v63, 11, 1
	v_and_b32 v89, v89, v62
	s_waitcnt lgkmcnt(10)
	v_mfma_f32_32x32x16_bf16 v[34:49], v[122:125], v[54:57], v[34:49]
	v_exp_f32_e32 v54, v90
	v_bfe_i32 v90, v63, 16, 1
	v_and_b32 v90, v90, v54
	v_exp_f32_e32 v54, v91
	v_bfe_i32 v91, v63, 17, 1
	v_and_b32 v91, v91, v54
	v_exp_f32_e32 v54, v92
	v_bfe_i32 v92, v63, 18, 1
	v_and_b32 v92, v92, v54
	v_exp_f32_e32 v54, v93
	v_bfe_i32 v93, v63, 19, 1
	v_and_b32 v93, v93, v54
	s_waitcnt lgkmcnt(8)
	v_mfma_f32_32x32x16_bf16 v[18:33], v[122:125], v[50:53], v[18:33]
	v_exp_f32_e32 v50, v94
	v_bfe_i32 v94, v63, 24, 1
	v_and_b32 v94, v94, v50
	v_exp_f32_e32 v50, v95
	v_bfe_i32 v95, v63, 25, 1
	v_and_b32 v95, v95, v50
	v_exp_f32_e32 v50, v96
	v_bfe_i32 v96, v63, 26, 1
	v_and_b32 v96, v96, v50
	v_exp_f32_e32 v50, v97
	v_bfe_i32 v97, v63, 27, 1
	v_and_b32 v97, v97, v50
	v_lshl_add_u64 v[50:51], v[212:213], 0, -8
	global_load_dwordx2 v[208:209], v[50:51], off
	s_andn2_b64 vcc, exec, s[0:1]
	s_waitcnt vmcnt(3) lgkmcnt(0)
	s_barrier
	s_cbranch_vccnz .LBB0_2979
	s_waitcnt lgkmcnt(0)
	ds_read_b128 v[50:53], v231 offset:49248
	ds_read_b128 v[54:57], v231 offset:49216
	ds_read_b128 v[62:65], v231 offset:49184
	ds_read_b128 v[66:69], v231 offset:49152
	s_waitcnt lgkmcnt(3)
	v_pk_mul_f32 v[48:49], v[48:49], v[52:53]
	s_waitcnt lgkmcnt(2)
	v_pk_mul_f32 v[44:45], v[44:45], v[56:57]
	s_waitcnt lgkmcnt(1)
	v_pk_mul_f32 v[40:41], v[40:41], v[64:65]
	s_waitcnt lgkmcnt(0)
	v_pk_mul_f32 v[36:37], v[36:37], v[68:69]
	v_pk_mul_f32 v[46:47], v[46:47], v[50:51]
	v_pk_mul_f32 v[42:43], v[42:43], v[54:55]
	v_pk_mul_f32 v[38:39], v[38:39], v[62:63]
	v_pk_mul_f32 v[34:35], v[34:35], v[66:67]
	v_pk_mul_f32 v[32:33], v[32:33], v[52:53]
	v_pk_mul_f32 v[28:29], v[28:29], v[56:57]
	v_pk_mul_f32 v[24:25], v[24:25], v[64:65]
	v_pk_mul_f32 v[20:21], v[20:21], v[68:69]
	v_pk_mul_f32 v[30:31], v[30:31], v[50:51]
	v_pk_mul_f32 v[26:27], v[26:27], v[54:55]
	v_pk_mul_f32 v[22:23], v[22:23], v[62:63]
	v_pk_mul_f32 v[18:19], v[18:19], v[66:67]

.LBB0_2982:
	v_lshrrev_b32_e32 v90, v232, v206
	v_lshrrev_b32_e32 v91, v232, v207
	s_waitcnt lgkmcnt(14)
	v_mfma_f32_32x32x16_bf16 v[34:49], v[142:145], v[158:161], v[34:49]
	v_exp_f32_e32 v82, v66
	v_bfe_i32 v66, v90, 0, 1
	v_and_b32 v66, v66, v82
	v_exp_f32_e32 v82, v67
	v_bfe_i32 v67, v90, 1, 1
	v_and_b32 v67, v67, v82
	v_exp_f32_e32 v82, v68
	v_bfe_i32 v68, v90, 2, 1
	v_and_b32 v68, v68, v82
	v_exp_f32_e32 v82, v69
	v_bfe_i32 v69, v90, 3, 1
	v_and_b32 v69, v69, v82
	s_waitcnt lgkmcnt(12)
	v_mfma_f32_32x32x16_bf16 v[18:33], v[142:145], v[154:157], v[18:33]
	v_exp_f32_e32 v82, v70
	v_bfe_i32 v70, v90, 8, 1
	v_and_b32 v70, v70, v82
	v_exp_f32_e32 v82, v71
	v_bfe_i32 v71, v90, 9, 1
	v_and_b32 v71, v71, v82
	v_exp_f32_e32 v82, v72
	v_bfe_i32 v72, v90, 10, 1
	v_and_b32 v72, v72, v82
	v_exp_f32_e32 v82, v73
	v_bfe_i32 v73, v90, 11, 1
	v_and_b32 v73, v73, v82
	v_add_u32_e32 v92, s25, v235
	ds_read_b128 v[82:85], v92
	ds_read_b128 v[166:169], v92 offset:512
	s_waitcnt lgkmcnt(12)
	v_mfma_f32_32x32x16_bf16 v[34:49], v[138:141], v[150:153], v[34:49]
	v_exp_f32_e32 v93, v74
	v_bfe_i32 v74, v90, 16, 1
	v_and_b32 v74, v74, v93
	v_exp_f32_e32 v93, v75
	v_bfe_i32 v75, v90, 17, 1
	v_and_b32 v75, v75, v93
	v_exp_f32_e32 v93, v76
	v_bfe_i32 v76, v90, 18, 1
	v_and_b32 v76, v76, v93
	v_exp_f32_e32 v93, v77
	v_bfe_i32 v77, v90, 19, 1
	v_and_b32 v77, v77, v93
	ds_read_b128 v[170:173], v92 offset:2048
	ds_read_b128 v[158:161], v92 offset:2560
	s_waitcnt lgkmcnt(12)
	v_mfma_f32_32x32x16_bf16 v[18:33], v[138:141], v[146:149], v[18:33]
	v_exp_f32_e32 v93, v78
	v_bfe_i32 v78, v90, 24, 1
	v_and_b32 v78, v78, v93
	v_exp_f32_e32 v93, v79
	v_bfe_i32 v79, v90, 25, 1
	v_and_b32 v79, v79, v93
	v_exp_f32_e32 v93, v80
	v_bfe_i32 v80, v90, 26, 1
	v_and_b32 v80, v80, v93
	v_exp_f32_e32 v93, v81
	v_bfe_i32 v81, v90, 27, 1
	v_and_b32 v81, v81, v93
	ds_read_b128 v[162:165], v92 offset:4096
	ds_read_b128 v[150:153], v92 offset:4608
	s_waitcnt lgkmcnt(12)
	v_mfma_f32_32x32x16_bf16 v[34:49], v[134:137], v[106:109], v[34:49]
	v_exp_f32_e32 v90, v50
	v_bfe_i32 v50, v91, 0, 1
	v_and_b32 v50, v50, v90
	v_exp_f32_e32 v90, v51
	v_bfe_i32 v51, v91, 1, 1
	v_and_b32 v51, v51, v90
	v_exp_f32_e32 v90, v52
	v_bfe_i32 v52, v91, 2, 1
	v_and_b32 v52, v52, v90
	v_exp_f32_e32 v90, v53
	v_bfe_i32 v53, v91, 3, 1
	v_and_b32 v53, v53, v90
	ds_read_b128 v[154:157], v92 offset:6144
	ds_read_b128 v[146:149], v92 offset:6656
	s_waitcnt lgkmcnt(12)
	v_mfma_f32_32x32x16_bf16 v[18:33], v[134:137], v[102:105], v[18:33]
	v_exp_f32_e32 v90, v54
	v_bfe_i32 v54, v91, 8, 1
	v_and_b32 v54, v54, v90
	v_exp_f32_e32 v90, v55
	v_bfe_i32 v55, v91, 9, 1
	v_and_b32 v55, v55, v90
	v_exp_f32_e32 v90, v56
	v_bfe_i32 v56, v91, 10, 1
	v_and_b32 v56, v56, v90
	v_exp_f32_e32 v90, v57
	v_bfe_i32 v57, v91, 11, 1
	v_and_b32 v57, v57, v90
	s_waitcnt lgkmcnt(10)
	v_mfma_f32_32x32x16_bf16 v[34:49], v[122:125], v[98:101], v[34:49]
	v_exp_f32_e32 v90, v58
	v_bfe_i32 v58, v91, 16, 1
	v_and_b32 v58, v58, v90
	v_exp_f32_e32 v90, v59
	v_bfe_i32 v59, v91, 17, 1
	v_and_b32 v59, v59, v90
	v_exp_f32_e32 v90, v60
	v_bfe_i32 v60, v91, 18, 1
	v_and_b32 v60, v60, v90
	v_exp_f32_e32 v90, v61
	v_bfe_i32 v61, v91, 19, 1
	v_and_b32 v61, v61, v90
	s_waitcnt lgkmcnt(8)
	v_mfma_f32_32x32x16_bf16 v[18:33], v[122:125], v[86:89], v[18:33]
	v_exp_f32_e32 v86, v62
	v_bfe_i32 v62, v91, 24, 1
	v_and_b32 v62, v62, v86
	v_exp_f32_e32 v86, v63
	v_bfe_i32 v63, v91, 25, 1
	v_and_b32 v63, v63, v86
	v_exp_f32_e32 v86, v64
	v_bfe_i32 v64, v91, 26, 1
	v_and_b32 v64, v64, v86
	v_exp_f32_e32 v86, v65
	v_bfe_i32 v65, v91, 27, 1
	v_and_b32 v65, v65, v86
	global_load_dwordx2 v[206:207], v[212:213], off
	s_andn2_b64 vcc, exec, s[0:1]
	s_waitcnt vmcnt(3) lgkmcnt(0)
	s_barrier
	s_cbranch_vccnz .LBB0_2984
	s_waitcnt lgkmcnt(0)
	ds_read_b128 v[86:89], v231 offset:49248
	ds_read_b128 v[90:93], v231 offset:49216
	ds_read_b128 v[94:97], v231 offset:49184
	ds_read_b128 v[98:101], v231 offset:49152
	s_waitcnt lgkmcnt(3)
	v_pk_mul_f32 v[48:49], v[48:49], v[88:89]
	s_waitcnt lgkmcnt(2)
	v_pk_mul_f32 v[44:45], v[44:45], v[92:93]
	s_waitcnt lgkmcnt(1)
	v_pk_mul_f32 v[40:41], v[40:41], v[96:97]
	s_waitcnt lgkmcnt(0)
	v_pk_mul_f32 v[36:37], v[36:37], v[100:101]
	v_pk_mul_f32 v[46:47], v[46:47], v[86:87]
	v_pk_mul_f32 v[42:43], v[42:43], v[90:91]
	v_pk_mul_f32 v[38:39], v[38:39], v[94:95]
	v_pk_mul_f32 v[34:35], v[34:35], v[98:99]
	v_pk_mul_f32 v[32:33], v[32:33], v[88:89]
	v_pk_mul_f32 v[28:29], v[28:29], v[92:93]
	v_pk_mul_f32 v[24:25], v[24:25], v[96:97]
	v_pk_mul_f32 v[20:21], v[20:21], v[100:101]
	v_pk_mul_f32 v[30:31], v[30:31], v[86:87]
	v_pk_mul_f32 v[26:27], v[26:27], v[90:91]
	v_pk_mul_f32 v[22:23], v[22:23], v[94:95]
	v_pk_mul_f32 v[18:19], v[18:19], v[98:99]

.LBB0_2996:
	v_lshrrev_b32_e32 v62, v232, v208
	v_lshrrev_b32_e32 v63, v232, v209
	s_waitcnt lgkmcnt(14)
	v_mfma_f32_32x32x16_bf16 v[34:49], v[142:145], v[178:181], v[34:49]
	v_exp_f32_e32 v58, v98
	v_bfe_i32 v98, v62, 0, 1
	v_and_b32 v98, v98, v58
	v_exp_f32_e32 v58, v99
	v_bfe_i32 v99, v62, 1, 1
	v_and_b32 v99, v99, v58
	v_exp_f32_e32 v58, v100
	v_bfe_i32 v100, v62, 2, 1
	v_and_b32 v100, v100, v58
	v_exp_f32_e32 v58, v101
	v_bfe_i32 v101, v62, 3, 1
	v_and_b32 v101, v101, v58
	s_waitcnt lgkmcnt(12)
	v_mfma_f32_32x32x16_bf16 v[18:33], v[142:145], v[174:177], v[18:33]
	v_exp_f32_e32 v58, v102
	v_bfe_i32 v102, v62, 8, 1
	v_and_b32 v102, v102, v58
	v_exp_f32_e32 v58, v103
	v_bfe_i32 v103, v62, 9, 1
	v_and_b32 v103, v103, v58
	v_exp_f32_e32 v58, v104
	v_bfe_i32 v104, v62, 10, 1
	v_and_b32 v104, v104, v58
	v_exp_f32_e32 v58, v105
	v_bfe_i32 v105, v62, 11, 1
	v_and_b32 v105, v105, v58
	v_add_u32_e32 v64, s34, v235
	ds_read_b128 v[58:61], v64
	ds_read_b128 v[146:149], v64 offset:512
	s_waitcnt lgkmcnt(12)
	v_mfma_f32_32x32x16_bf16 v[34:49], v[138:141], v[166:169], v[34:49]
	v_exp_f32_e32 v65, v106
	v_bfe_i32 v106, v62, 16, 1
	v_and_b32 v106, v106, v65
	v_exp_f32_e32 v65, v107
	v_bfe_i32 v107, v62, 17, 1
	v_and_b32 v107, v107, v65
	v_exp_f32_e32 v65, v108
	v_bfe_i32 v108, v62, 18, 1
	v_and_b32 v108, v108, v65
	v_exp_f32_e32 v65, v109
	v_bfe_i32 v109, v62, 19, 1
	v_and_b32 v109, v109, v65
	ds_read_b128 v[170:173], v64 offset:2048
	ds_read_b128 v[158:161], v64 offset:2560
	s_waitcnt lgkmcnt(12)
	v_mfma_f32_32x32x16_bf16 v[18:33], v[138:141], v[74:77], v[18:33]
	v_exp_f32_e32 v65, v110
	v_bfe_i32 v110, v62, 24, 1
	v_and_b32 v110, v110, v65
	v_exp_f32_e32 v65, v111
	v_bfe_i32 v111, v62, 25, 1
	v_and_b32 v111, v111, v65
	v_exp_f32_e32 v65, v112
	v_bfe_i32 v112, v62, 26, 1
	v_and_b32 v112, v112, v65
	v_exp_f32_e32 v65, v113
	v_bfe_i32 v113, v62, 27, 1
	v_and_b32 v113, v113, v65
	ds_read_b128 v[174:177], v64 offset:4096
	ds_read_b128 v[162:165], v64 offset:4608
	s_waitcnt lgkmcnt(12)
	v_mfma_f32_32x32x16_bf16 v[34:49], v[134:137], v[70:73], v[34:49]
	v_exp_f32_e32 v62, v82
	v_bfe_i32 v82, v63, 0, 1
	v_and_b32 v82, v82, v62
	v_exp_f32_e32 v62, v83
	v_bfe_i32 v83, v63, 1, 1
	v_and_b32 v83, v83, v62
	v_exp_f32_e32 v62, v84
	v_bfe_i32 v84, v63, 2, 1
	v_and_b32 v84, v84, v62
	v_exp_f32_e32 v62, v85
	v_bfe_i32 v85, v63, 3, 1
	v_and_b32 v85, v85, v62
	ds_read_b128 v[178:181], v64 offset:6144
	ds_read_b128 v[166:169], v64 offset:6656
	s_waitcnt lgkmcnt(12)
	v_mfma_f32_32x32x16_bf16 v[18:33], v[134:137], v[66:69], v[18:33]
	v_exp_f32_e32 v62, v86
	v_bfe_i32 v86, v63, 8, 1
	v_and_b32 v86, v86, v62
	v_exp_f32_e32 v62, v87
	v_bfe_i32 v87, v63, 9, 1
	v_and_b32 v87, v87, v62
	v_exp_f32_e32 v62, v88
	v_bfe_i32 v88, v63, 10, 1
	v_and_b32 v88, v88, v62
	v_exp_f32_e32 v62, v89
	v_bfe_i32 v89, v63, 11, 1
	v_and_b32 v89, v89, v62
	s_waitcnt lgkmcnt(10)
	v_mfma_f32_32x32x16_bf16 v[34:49], v[122:125], v[54:57], v[34:49]
	v_exp_f32_e32 v54, v90
	v_bfe_i32 v90, v63, 16, 1
	v_and_b32 v90, v90, v54
	v_exp_f32_e32 v54, v91
	v_bfe_i32 v91, v63, 17, 1
	v_and_b32 v91, v91, v54
	v_exp_f32_e32 v54, v92
	v_bfe_i32 v92, v63, 18, 1
	v_and_b32 v92, v92, v54
	v_exp_f32_e32 v54, v93
	v_bfe_i32 v93, v63, 19, 1
	v_and_b32 v93, v93, v54
	s_waitcnt lgkmcnt(8)
	v_mfma_f32_32x32x16_bf16 v[18:33], v[122:125], v[50:53], v[18:33]
	v_exp_f32_e32 v50, v94
	v_bfe_i32 v94, v63, 24, 1
	v_and_b32 v94, v94, v50
	v_exp_f32_e32 v50, v95
	v_bfe_i32 v95, v63, 25, 1
	v_and_b32 v95, v95, v50
	v_exp_f32_e32 v50, v96
	v_bfe_i32 v96, v63, 26, 1
	v_and_b32 v96, v96, v50
	v_exp_f32_e32 v50, v97
	v_bfe_i32 v97, v63, 27, 1
	v_and_b32 v97, v97, v50
	s_lshr_b32 s68, s20, 3
	v_lshl_add_u64 v[50:51], v[204:205], 0, s[68:69]
	v_lshl_add_u64 v[50:51], v[50:51], 0, -8
	global_load_dwordx2 v[182:183], v[50:51], off
	s_andn2_b64 vcc, exec, s[0:1]
	s_waitcnt vmcnt(2) lgkmcnt(0)
	s_barrier
	s_cbranch_vccnz .LBB0_2998
	s_waitcnt lgkmcnt(0)
	ds_read_b128 v[50:53], v231 offset:49248
	ds_read_b128 v[54:57], v231 offset:49216
	ds_read_b128 v[62:65], v231 offset:49184
	ds_read_b128 v[66:69], v231 offset:49152
	s_waitcnt lgkmcnt(3)
	v_pk_mul_f32 v[48:49], v[48:49], v[52:53]
	s_waitcnt lgkmcnt(2)
	v_pk_mul_f32 v[44:45], v[44:45], v[56:57]
	s_waitcnt lgkmcnt(1)
	v_pk_mul_f32 v[40:41], v[40:41], v[64:65]
	s_waitcnt lgkmcnt(0)
	v_pk_mul_f32 v[36:37], v[36:37], v[68:69]
	v_pk_mul_f32 v[46:47], v[46:47], v[50:51]
	v_pk_mul_f32 v[42:43], v[42:43], v[54:55]
	v_pk_mul_f32 v[38:39], v[38:39], v[62:63]
	v_pk_mul_f32 v[34:35], v[34:35], v[66:67]
	v_pk_mul_f32 v[32:33], v[32:33], v[52:53]
	v_pk_mul_f32 v[28:29], v[28:29], v[56:57]
	v_pk_mul_f32 v[24:25], v[24:25], v[64:65]
	v_pk_mul_f32 v[20:21], v[20:21], v[68:69]
	v_pk_mul_f32 v[30:31], v[30:31], v[50:51]
	v_pk_mul_f32 v[26:27], v[26:27], v[54:55]
	v_pk_mul_f32 v[22:23], v[22:23], v[62:63]
	v_pk_mul_f32 v[18:19], v[18:19], v[66:67]

.LBB0_3001:
	v_lshrrev_b32_e32 v90, v232, v206
	v_lshrrev_b32_e32 v91, v232, v207
	s_waitcnt lgkmcnt(14)
	v_mfma_f32_32x32x16_bf16 v[34:49], v[142:145], v[154:157], v[34:49]
	v_exp_f32_e32 v92, v66
	v_bfe_i32 v66, v90, 0, 1
	v_and_b32 v66, v66, v92
	v_exp_f32_e32 v92, v67
	v_bfe_i32 v67, v90, 1, 1
	v_and_b32 v67, v67, v92
	v_exp_f32_e32 v92, v68
	v_bfe_i32 v68, v90, 2, 1
	v_and_b32 v68, v68, v92
	v_exp_f32_e32 v92, v69
	v_bfe_i32 v69, v90, 3, 1
	v_and_b32 v69, v69, v92
	s_waitcnt lgkmcnt(12)
	v_mfma_f32_32x32x16_bf16 v[18:33], v[142:145], v[150:153], v[18:33]
	v_exp_f32_e32 v92, v70
	v_bfe_i32 v70, v90, 8, 1
	v_and_b32 v70, v70, v92
	v_exp_f32_e32 v92, v71
	v_bfe_i32 v71, v90, 9, 1
	v_and_b32 v71, v71, v92
	v_exp_f32_e32 v92, v72
	v_bfe_i32 v72, v90, 10, 1
	v_and_b32 v72, v72, v92
	v_exp_f32_e32 v92, v73
	v_bfe_i32 v73, v90, 11, 1
	v_and_b32 v73, v73, v92
	v_add_u32_e32 v92, s20, v235
	ds_read_b128 v[158:161], v92
	ds_read_b128 v[150:153], v92 offset:512
	s_waitcnt lgkmcnt(12)
	v_mfma_f32_32x32x16_bf16 v[34:49], v[138:141], v[146:149], v[34:49]
	v_exp_f32_e32 v93, v74
	v_bfe_i32 v74, v90, 16, 1
	v_and_b32 v74, v74, v93
	v_exp_f32_e32 v93, v75
	v_bfe_i32 v75, v90, 17, 1
	v_and_b32 v75, v75, v93
	v_exp_f32_e32 v93, v76
	v_bfe_i32 v76, v90, 18, 1
	v_and_b32 v76, v76, v93
	v_exp_f32_e32 v93, v77
	v_bfe_i32 v77, v90, 19, 1
	v_and_b32 v77, v77, v93
	ds_read_b128 v[166:169], v92 offset:2048
	ds_read_b128 v[146:149], v92 offset:2560
	s_waitcnt lgkmcnt(12)
	v_mfma_f32_32x32x16_bf16 v[18:33], v[138:141], v[106:109], v[18:33]
	v_exp_f32_e32 v93, v78
	v_bfe_i32 v78, v90, 24, 1
	v_and_b32 v78, v78, v93
	v_exp_f32_e32 v93, v79
	v_bfe_i32 v79, v90, 25, 1
	v_and_b32 v79, v79, v93
	v_exp_f32_e32 v93, v80
	v_bfe_i32 v80, v90, 26, 1
	v_and_b32 v80, v80, v93
	v_exp_f32_e32 v93, v81
	v_bfe_i32 v81, v90, 27, 1
	v_and_b32 v81, v81, v93
	ds_read_b128 v[170:173], v92 offset:4096
	ds_read_b128 v[154:157], v92 offset:4608
	s_waitcnt lgkmcnt(12)
	v_mfma_f32_32x32x16_bf16 v[34:49], v[134:137], v[102:105], v[34:49]
	v_exp_f32_e32 v90, v50
	v_bfe_i32 v50, v91, 0, 1
	v_and_b32 v50, v50, v90
	v_exp_f32_e32 v90, v51
	v_bfe_i32 v51, v91, 1, 1
	v_and_b32 v51, v51, v90
	v_exp_f32_e32 v90, v52
	v_bfe_i32 v52, v91, 2, 1
	v_and_b32 v52, v52, v90
	v_exp_f32_e32 v90, v53
	v_bfe_i32 v53, v91, 3, 1
	v_and_b32 v53, v53, v90
	ds_read_b128 v[174:177], v92 offset:6144
	ds_read_b128 v[162:165], v92 offset:6656
	s_waitcnt lgkmcnt(12)
	v_mfma_f32_32x32x16_bf16 v[18:33], v[134:137], v[98:101], v[18:33]
	v_exp_f32_e32 v90, v54
	v_bfe_i32 v54, v91, 8, 1
	v_and_b32 v54, v54, v90
	v_exp_f32_e32 v90, v55
	v_bfe_i32 v55, v91, 9, 1
	v_and_b32 v55, v55, v90
	v_exp_f32_e32 v90, v56
	v_bfe_i32 v56, v91, 10, 1
	v_and_b32 v56, v56, v90
	v_exp_f32_e32 v90, v57
	v_bfe_i32 v57, v91, 11, 1
	v_and_b32 v57, v57, v90
	s_waitcnt lgkmcnt(10)
	v_mfma_f32_32x32x16_bf16 v[34:49], v[122:125], v[86:89], v[34:49]
	v_exp_f32_e32 v86, v58
	v_bfe_i32 v58, v91, 16, 1
	v_and_b32 v58, v58, v86
	v_exp_f32_e32 v86, v59
	v_bfe_i32 v59, v91, 17, 1
	v_and_b32 v59, v59, v86
	v_exp_f32_e32 v86, v60
	v_bfe_i32 v60, v91, 18, 1
	v_and_b32 v60, v60, v86
	v_exp_f32_e32 v86, v61
	v_bfe_i32 v61, v91, 19, 1
	v_and_b32 v61, v61, v86
	s_waitcnt lgkmcnt(8)
	v_mfma_f32_32x32x16_bf16 v[18:33], v[122:125], v[82:85], v[18:33]
	v_exp_f32_e32 v82, v62
	v_bfe_i32 v62, v91, 24, 1
	v_and_b32 v62, v62, v82
	v_exp_f32_e32 v82, v63
	v_bfe_i32 v63, v91, 25, 1
	v_and_b32 v63, v63, v82
	v_exp_f32_e32 v82, v64
	v_bfe_i32 v64, v91, 26, 1
	v_and_b32 v64, v64, v82
	v_exp_f32_e32 v82, v65
	v_bfe_i32 v65, v91, 27, 1
	v_and_b32 v65, v65, v82
	s_waitcnt vmcnt(0) lgkmcnt(0)
	s_barrier
	s_andn2_b64 vcc, exec, s[0:1]
	s_cbranch_vccnz .LBB0_3003
	s_waitcnt lgkmcnt(0)
	ds_read_b128 v[82:85], v231 offset:49248
	ds_read_b128 v[86:89], v231 offset:49216
	ds_read_b128 v[90:93], v231 offset:49184
	ds_read_b128 v[94:97], v231 offset:49152
	s_waitcnt lgkmcnt(3)
	v_pk_mul_f32 v[48:49], v[48:49], v[84:85]
	s_waitcnt lgkmcnt(2)
	v_pk_mul_f32 v[44:45], v[44:45], v[88:89]
	s_waitcnt lgkmcnt(1)
	v_pk_mul_f32 v[40:41], v[40:41], v[92:93]
	s_waitcnt lgkmcnt(0)
	v_pk_mul_f32 v[36:37], v[36:37], v[96:97]
	v_pk_mul_f32 v[46:47], v[46:47], v[82:83]
	v_pk_mul_f32 v[42:43], v[42:43], v[86:87]
	v_pk_mul_f32 v[38:39], v[38:39], v[90:91]
	v_pk_mul_f32 v[34:35], v[34:35], v[94:95]
	v_pk_mul_f32 v[32:33], v[32:33], v[84:85]
	v_pk_mul_f32 v[28:29], v[28:29], v[88:89]
	v_pk_mul_f32 v[24:25], v[24:25], v[92:93]
	v_pk_mul_f32 v[20:21], v[20:21], v[96:97]
	v_pk_mul_f32 v[30:31], v[30:31], v[82:83]
	v_pk_mul_f32 v[26:27], v[26:27], v[86:87]
	v_pk_mul_f32 v[22:23], v[22:23], v[90:91]
	v_pk_mul_f32 v[18:19], v[18:19], v[94:95]

.LBB0_3006:
	v_lshrrev_b32_e32 v50, v232, v182
	v_lshrrev_b32_e32 v51, v232, v183
	s_waitcnt lgkmcnt(14)
	v_mfma_f32_32x32x16_bf16 v[34:49], v[142:145], v[110:113], v[34:49]
	v_exp_f32_e32 v52, v82
	v_bfe_i32 v82, v50, 0, 1
	v_and_b32 v82, v82, v52
	v_exp_f32_e32 v52, v83
	v_bfe_i32 v83, v50, 1, 1
	v_and_b32 v83, v83, v52
	v_exp_f32_e32 v52, v84
	v_bfe_i32 v84, v50, 2, 1
	v_and_b32 v84, v84, v52
	v_exp_f32_e32 v52, v85
	v_bfe_i32 v85, v50, 3, 1
	v_and_b32 v85, v85, v52
	s_waitcnt lgkmcnt(12)
	v_mfma_f32_32x32x16_bf16 v[18:33], v[142:145], v[106:109], v[18:33]
	v_exp_f32_e32 v52, v86
	v_bfe_i32 v86, v50, 8, 1
	v_and_b32 v86, v86, v52
	v_exp_f32_e32 v52, v87
	v_bfe_i32 v87, v50, 9, 1
	v_and_b32 v87, v87, v52
	v_exp_f32_e32 v52, v88
	v_bfe_i32 v88, v50, 10, 1
	v_and_b32 v88, v88, v52
	v_exp_f32_e32 v52, v89
	v_bfe_i32 v89, v50, 11, 1
	v_and_b32 v89, v89, v52
	s_waitcnt lgkmcnt(10)
	v_mfma_f32_32x32x16_bf16 v[34:49], v[138:141], v[102:105], v[34:49]
	v_exp_f32_e32 v52, v90
	v_bfe_i32 v90, v50, 16, 1
	v_and_b32 v90, v90, v52
	v_exp_f32_e32 v52, v91
	v_bfe_i32 v91, v50, 17, 1
	v_and_b32 v91, v91, v52
	v_exp_f32_e32 v52, v92
	v_bfe_i32 v92, v50, 18, 1
	v_and_b32 v92, v92, v52
	v_exp_f32_e32 v52, v93
	v_bfe_i32 v93, v50, 19, 1
	v_and_b32 v93, v93, v52
	s_waitcnt lgkmcnt(8)
	v_mfma_f32_32x32x16_bf16 v[18:33], v[138:141], v[98:101], v[18:33]
	v_exp_f32_e32 v52, v94
	v_bfe_i32 v94, v50, 24, 1
	v_and_b32 v94, v94, v52
	v_exp_f32_e32 v52, v95
	v_bfe_i32 v95, v50, 25, 1
	v_and_b32 v95, v95, v52
	v_exp_f32_e32 v52, v96
	v_bfe_i32 v96, v50, 26, 1
	v_and_b32 v96, v96, v52
	v_exp_f32_e32 v52, v97
	v_bfe_i32 v97, v50, 27, 1
	v_and_b32 v97, v97, v52
	s_waitcnt lgkmcnt(6)
	v_mfma_f32_32x32x16_bf16 v[34:49], v[134:137], v[78:81], v[34:49]
	v_exp_f32_e32 v50, v2
	v_bfe_i32 v2, v51, 0, 1
	v_and_b32 v2, v2, v50
	v_exp_f32_e32 v50, v3
	v_bfe_i32 v3, v51, 1, 1
	v_and_b32 v3, v3, v50
	v_exp_f32_e32 v50, v4
	v_bfe_i32 v4, v51, 2, 1
	v_and_b32 v4, v4, v50
	v_exp_f32_e32 v50, v5
	v_bfe_i32 v5, v51, 3, 1
	v_and_b32 v5, v5, v50
	s_waitcnt lgkmcnt(4)
	v_mfma_f32_32x32x16_bf16 v[18:33], v[134:137], v[74:77], v[18:33]
	v_exp_f32_e32 v50, v6
	v_bfe_i32 v6, v51, 8, 1
	v_and_b32 v6, v6, v50
	v_exp_f32_e32 v50, v7
	v_bfe_i32 v7, v51, 9, 1
	v_and_b32 v7, v7, v50
	v_exp_f32_e32 v50, v8
	v_bfe_i32 v8, v51, 10, 1
	v_and_b32 v8, v8, v50
	v_exp_f32_e32 v50, v9
	v_bfe_i32 v9, v51, 11, 1
	v_and_b32 v9, v9, v50
	s_waitcnt lgkmcnt(2)
	v_mfma_f32_32x32x16_bf16 v[34:49], v[122:125], v[70:73], v[34:49]
	v_exp_f32_e32 v50, v10
	v_bfe_i32 v10, v51, 16, 1
	v_and_b32 v10, v10, v50
	v_exp_f32_e32 v50, v11
	v_bfe_i32 v11, v51, 17, 1
	v_and_b32 v11, v11, v50
	v_exp_f32_e32 v50, v12
	v_bfe_i32 v12, v51, 18, 1
	v_and_b32 v12, v12, v50
	v_exp_f32_e32 v50, v13
	v_bfe_i32 v13, v51, 19, 1
	v_and_b32 v13, v13, v50
	s_waitcnt lgkmcnt(0)
	v_mfma_f32_32x32x16_bf16 v[18:33], v[122:125], v[66:69], v[18:33]
	v_exp_f32_e32 v50, v14
	v_bfe_i32 v14, v51, 24, 1
	v_and_b32 v14, v14, v50
	v_exp_f32_e32 v50, v15
	v_bfe_i32 v15, v51, 25, 1
	v_and_b32 v15, v15, v50
	v_exp_f32_e32 v50, v16
	v_bfe_i32 v16, v51, 26, 1
	v_and_b32 v16, v16, v50
	v_exp_f32_e32 v50, v17
	v_bfe_i32 v17, v51, 27, 1
	v_and_b32 v17, v17, v50
	s_andn2_b64 vcc, exec, s[0:1]
	s_cbranch_vccnz .LBB0_3008
	s_waitcnt lgkmcnt(0)
	ds_read_b128 v[50:53], v231 offset:49248
	ds_read_b128 v[54:57], v231 offset:49216
	ds_read_b128 v[58:61], v231 offset:49184
	ds_read_b128 v[62:65], v231 offset:49152
	s_waitcnt lgkmcnt(3)
	v_pk_mul_f32 v[48:49], v[48:49], v[52:53]
	s_waitcnt lgkmcnt(2)
	v_pk_mul_f32 v[44:45], v[44:45], v[56:57]
	s_waitcnt lgkmcnt(1)
	v_pk_mul_f32 v[40:41], v[40:41], v[60:61]
	s_waitcnt lgkmcnt(0)
	v_pk_mul_f32 v[36:37], v[36:37], v[64:65]
	v_pk_mul_f32 v[46:47], v[46:47], v[50:51]
	v_pk_mul_f32 v[42:43], v[42:43], v[54:55]
	v_pk_mul_f32 v[38:39], v[38:39], v[58:59]
	v_pk_mul_f32 v[34:35], v[34:35], v[62:63]
	v_pk_mul_f32 v[32:33], v[32:33], v[52:53]
	v_pk_mul_f32 v[28:29], v[28:29], v[56:57]
	v_pk_mul_f32 v[24:25], v[24:25], v[60:61]
	v_pk_mul_f32 v[20:21], v[20:21], v[64:65]
	v_pk_mul_f32 v[30:31], v[30:31], v[50:51]
	v_pk_mul_f32 v[26:27], v[26:27], v[54:55]
	v_pk_mul_f32 v[22:23], v[22:23], v[58:59]
	v_pk_mul_f32 v[18:19], v[18:19], v[62:63]
